# combination: barrier top-generation polling + aligned attention loop + odd-head row-half relabel on the phase-3 combo
# speedup vs baseline: 1.0106x; 1.0101x over previous
.LBB0_877:
	s_or_b64 exec, exec, s[0:1]
	v_lshrrev_b32_e32 v244, 1, v254
	v_and_b32_e32 v244, 0x80, v244
	v_xor_b32_e32 v244, v244, v254
	v_mov_b32_e32 v1, v244
	s_waitcnt lgkmcnt(0)
	s_barrier
	s_cmp_lg_u32 0, -1
	v_lshrrev_b32_e32 v5, 2, v1
	v_lshrrev_b32_e32 v2, 5, v1
	v_lshlrev_b32_e32 v4, 2, v1
	v_and_b32_e32 v6, 2, v5
	v_and_or_b32 v4, v4, 12, v6
	v_xor_b32_e32 v6, v2, v5
	v_and_or_b32 v4, v6, 1, v4
	v_lshrrev_b32_e32 v6, 1, v1
	v_and_b32_e32 v0, 31, v1
	v_xor_b32_e32 v2, v2, v6
	v_lshlrev_b32_e32 v7, 7, v0
	v_lshlrev_b32_e32 v2, 4, v2
	v_lshlrev_b32_e32 v6, 3, v1
	v_bfe_u32 v3, v1, 5, 1
	v_and_or_b32 v2, v2, 16, v7
	v_and_b32_e32 v7, 0x60, v6
	v_bfe_u32 v8, v1, 2, 2
	v_and_b32_e32 v6, 8, v6
	s_cselect_b32 s0, 0, 0
	v_lshrrev_b32_e32 v9, 3, v1
	v_lshlrev_b32_e32 v12, 10, v3
	v_lshlrev_b32_e32 v13, 8, v8
	v_add_u32_e32 v6, s0, v6
	v_and_b32_e32 v10, 2, v9
	v_bfe_u32 v11, v1, 1, 1
	v_add3_u32 v6, v6, v12, v13
	v_or_b32_e32 v13, 2, v3
	v_lshlrev_b32_e32 v0, 8, v0
	v_bitop3_b32 v12, v10, v3, v11 bitop3:0x36
	v_bitop3_b32 v10, v10, v13, v11 bitop3:0x36
	v_lshl_or_b32 v198, v4, 4, v0
	v_lshlrev_b32_e32 v0, 4, v1
	v_lshlrev_b32_e32 v10, 4, v10
	s_movk_i32 s0, 0x800
	v_lshlrev_b32_e32 v8, 6, v8
	s_movk_i32 s16, 0x4000
	v_and_b32_e32 v0, 0x1f0, v0
	v_lshl_add_u32 v12, v12, 4, v6
	v_add3_u32 v6, v6, v10, s0
	v_xor_b32_e32 v10, 64, v8
	v_or3_b32 v199, v2, v7, s16
	v_lshl_or_b32 v2, v3, 9, v0
	v_mov_b32_e32 v0, 0
	v_add_u32_e32 v188, v12, v8
	v_add_u32_e32 v189, v6, v8
	v_add_u32_e32 v192, v12, v10
	v_add_u32_e32 v193, v6, v10
	v_xor_b32_e32 v10, 0x80, v8
	v_xor_b32_e32 v8, 0xc0, v8
	v_mov_b32_e32 v3, v0
	v_add_u32_e32 v196, v12, v8
	v_add_u32_e32 v197, v6, v8
	v_lshl_add_u64 v[162:163], s[36:37], 0, v[2:3]
	v_and_b32_e32 v2, 15, v1
	v_and_b32_e32 v5, 12, v5
	v_bfe_u32 v8, v1, 6, 2
	v_bitop3_b32 v2, v5, v2, v8 bitop3:0x36
	s_not_b32 s0, s2
	v_add_u32_e32 v3, 0x200, v1
	v_lshrrev_b32_e32 v4, 4, v1
	v_lshlrev_b32_e32 v2, 4, v2
	s_movk_i32 s7, 0x180
	s_add_i32 s17, s30, s0
	v_mad_u64_u32 v[164:165], s[0:1], v4, s7, v[2:3]
	v_bfe_u32 v7, v1, 4, 5
	v_lshrrev_b32_e32 v5, 4, v3
	s_mov_b32 s0, 0x1ffffe0
	v_add_u32_e32 v195, v6, v10
	s_movk_i32 s6, 0xc0
	v_ashrrev_i32_e32 v6, 6, v1
	v_ashrrev_i32_e32 v200, 8, v1
	v_and_or_b32 v5, v5, s0, v7
	v_xor_b32_e32 v1, v4, v1
	v_mad_u64_u32 v[166:167], s[0:1], v5, s7, v[2:3]
	v_mul_lo_u32 v5, v9, s6
	v_lshlrev_b32_e32 v1, 3, v1
	v_and_or_b32 v1, v1, 56, v5
	v_mov_b32_e32 v5, 0x100
	v_lshlrev_b32_e32 v4, 10, v6
	v_lshl_add_u32 v168, v1, 1, v5
	v_lshrrev_b32_e32 v1, 9, v3
	v_mul_u32_u24_e32 v1, 0x3000, v1
	v_mul_u32_u24_e32 v3, 0x180, v7
	v_add_u32_e32 v203, 0, v4
	s_mov_b32 s3, 0
	v_add_u32_e32 v194, v12, v10
	v_and_b32_e32 v201, 3, v6
	v_bfe_u32 v202, v6, 1, 1
	v_mov_b32_e32 v165, v0
	v_mov_b32_e32 v167, v0
	v_mov_b32_e32 v169, v0
	s_movk_i32 s36, 0x3000
	v_add3_u32 v170, v1, v3, v2
	v_mov_b32_e32 v171, v0
	s_movk_i32 s37, 0x1000
	s_movk_i32 s40, 0x2000
	v_add_u32_e32 v204, 0x2000, v203
	v_add_u32_e32 v205, 0x4000, v203
	s_mov_b64 s[0:1], 0x1dc06000
	s_mov_b32 s41, 0x8000
	s_mov_b64 s[6:7], 0x1dc0c000
	s_movk_i32 s44, 0xfe0
	s_movk_i32 s45, 0x2200
	s_mov_b32 s50, 0xc000
	s_mov_b32 s51, 0x10000
	s_mov_b32 s52, 0x14000
	s_mov_b32 s53, 0x18000
	v_mbcnt_hi_u32_b32 v191, -1, v186
	v_readfirstlane_b32 s74, v203
	v_readfirstlane_b32 s76, v244
	s_nop 0
	s_bfe_u32 s76, s76, 0x10007
	s_add_u32 s82, s74, 0x6000
	s_add_u32 s83, s74, 0x8000
	s_add_u32 s86, s74, 0xa000
	s_add_u32 s87, s74, 0x2000
	s_add_u32 s88, s74, 0x4000
	s_movk_i32 s77, 0x60
	s_movk_i32 s78, 0x80
	s_movk_i32 s79, 0xa0
	s_movk_i32 s80, 0xc0
	s_movk_i32 s81, 0xe0
	s_mov_b32 s54, 0
	s_branch .LBB0_879
